# hand-written weight/cache f32->bf16 transposing routine with 32-40 loads in flight per wave replaces the 7 compiled transposes
# speedup vs baseline: 1.0589x; 1.0589x over previous
; #define LAS __attribute__((address_space(3)))
; #define LAS __attribute__((address_space(3)))
; __device__ __forceinline__ unsigned pk2(float lo, float hi) { return pg8::cvt_pk_bf16(lo, hi); }
; __device__ __forceinline__ void convert_layer_caches(const Args& a, unsigned char* ws, LAS float* scr, int l, int gw, int NGW, int gt, int NGT, int lane) {
;     constexpr int C_CMV = 1024, C_CWV = 256;
;     for (int it = gw; it < C_CMV + C_CWV; it += NGW) {
;         int r = it;
;         if (r < C_CMV) { const int b = r / 32, r2 = r % 32, kb = r2 / 8, nb = r2 % 8; p0_transpose_item(a.in[7] + (size_t)(l * NBS + b) * 65536, 256, 256, nullptr, (bf16*)(ws + WS_MVT) + (size_t)(l * 40 + 8 + b) * 65536, 32 * nb, 32 * nb, 64 * kb, scr, lane); continue; } r -= C_CMV;
;         { const int b = r / 8, r2 = r % 8, kb = r2 / 4, nb = r2 % 4; p0_transpose_item(a.in[4] + (size_t)(l * NBS + b) * 16384, 128, 128, nullptr, (bf16*)(ws + WS_CWVT) + (size_t)(l * NBS + b) * 16384, 32 * nb, 32 * nb, 64 * kb, scr, lane); }
;     }
;     for (int i = gt; i < (524288 + 2097152) / 8; i += NGT) {
;         const float* src; bf16* dst;
;         if (i < 65536) { const size_t e = (size_t)l * 524288 + (size_t)i * 8; src = a.in[3] + e; dst = (bf16*)(ws + WS_CWK) + e; }
;         else { const int e = (i - 65536) * 8, b = e >> 16, rem = e & 65535; src = a.in[6] + (size_t)(l * NBS + b) * 65536 + rem; dst = (bf16*)(ws + WS_MK) + (size_t)(l * 40 + 8 + b) * 65536 + rem; }
;         const f32x4 x0 = __builtin_nontemporal_load((const f32x4*)src), x1 = __builtin_nontemporal_load((const f32x4*)(src + 4));
;         v4u o; o.x = pk2(x0.x, x0.y); o.y = pk2(x0.z, x0.w); o.z = pk2(x1.x, x1.y); o.w = pk2(x1.z, x1.w);
;         *(v4u*)dst = o;
;     }
; __global__ void __launch_bounds__(NWAVES * 64, 2) hymba_fwd(Args args) {
;     ...
;                 if (l + 1 < DEPTH && blockIdx.x >= 48) {
;                     int ln = lane, tn = tid; asm volatile("" : "+v"(ln), "+v"(tn));
;                     const int wk = ((int)blockIdx.x - 48) * NWAVES + wave, nwk = (G - 48) * NWAVES;
;                     convert_layer_weights(args, ws, (LAS float*)(lds + wave * 16384), l + 1, wk, nwk, ln, 12);
;                     convert_layer_caches(args, ws, (LAS float*)(lds + wave * 16384), l + 1, wk, nwk, ((int)blockIdx.x - 48) * (NWAVES * 64) + tn, (G - 48) * NWAVES * 64, ln);
.LBB0_46:
	s_cmp_gt_i32 s54, 15
	v_readlane_b32 s2, v255, 5
	s_cselect_b64 s[0:1], -1, 0
	v_readlane_b32 s3, v255, 6
	s_or_b64 s[0:1], s[2:3], s[0:1]
	s_and_b64 vcc, exec, s[0:1]
	s_cbranch_vccnz .LBB0_204
	v_readlane_b32 s0, v255, 19
	v_readlane_b32 s1, v255, 20
	s_add_i32 s4, s0, 1
	v_readlane_b32 s0, v251, 9
	v_and_b32_e32 v55, 63, v216
	v_mov_b32_e32 v1, v216
	v_readlane_b32 s1, v251, 10
	s_andn2_b64 vcc, exec, s[0:1]
	v_ashrrev_i32_e32 v18, 5, v55
	v_ashrrev_i32_e32 v19, 3, v55
	v_lshlrev_b32_e32 v0, 3, v55
	s_movk_i32 s0, 0x84
	v_mul_lo_u32 v20, v18, s0
	v_add_u32_e32 v21, 2, v18
	v_add_u32_e32 v22, 4, v18
	v_add_u32_e32 v23, 6, v18
	v_add_u32_e32 v24, 8, v18
	v_add_u32_e32 v25, 10, v18
	v_add_u32_e32 v26, 12, v18
	v_add_u32_e32 v27, 14, v18
	v_add_u32_e32 v28, 16, v18
	v_add_u32_e32 v29, 18, v18
	v_add_u32_e32 v30, 20, v18
	v_add_u32_e32 v31, 22, v18
	v_add_u32_e32 v32, 24, v18
	v_add_u32_e32 v33, 26, v18
	v_add_u32_e32 v34, 28, v18
	v_add_u32_e32 v35, 30, v18
	v_add_u32_e32 v36, 32, v18
	v_add_u32_e32 v37, 34, v18
	v_add_u32_e32 v38, 36, v18
	v_add_u32_e32 v39, 38, v18
	v_add_u32_e32 v40, 40, v18
	v_add_u32_e32 v41, 42, v18
	v_add_u32_e32 v42, 44, v18
	v_add_u32_e32 v43, 46, v18
	v_add_u32_e32 v44, 48, v18
	v_add_u32_e32 v45, 50, v18
	v_add_u32_e32 v46, 52, v18
	v_add_u32_e32 v47, 54, v18
	v_add_u32_e32 v48, 56, v18
	v_add_u32_e32 v49, 58, v18
	v_add_u32_e32 v50, 60, v18
	v_add_u32_e32 v51, 62, v18
	v_and_b32_e32 v0, 56, v0
	v_lshlrev_b32_e32 v56, 2, v19
	v_add_u32_e32 v52, 8, v19
	v_add_u32_e32 v53, 16, v19
	v_add_u32_e32 v54, 24, v19
	v_readlane_b32 s6, v251, 14
	s_cbranch_vccnz .LBB0_191
	s_lshl_b32 s100, s4, 8
	s_or_b32 s100, s100, 0x30000c
	s_mov_b32 s101, 1
	s_branch .Lcvt_entry
.Lcvt_ret1:
.LBB0_191:
	v_readlane_b32 s0, v251, 15
	v_readlane_b32 s1, v251, 16
	s_andn2_b64 vcc, exec, s[0:1]
	s_mul_i32 s5, s4, 40
	s_cbranch_vccnz .LBB0_198
	s_lshl_b32 s100, s4, 8
	s_or_b32 s100, s100, 0x300060
	s_mov_b32 s101, 2
	s_branch .Lcvt_entry
.Lcvt_ret2:
.LBB0_198:
	v_readlane_b32 s0, v251, 13
	s_nop 1
	v_add_u32_e32 v0, s0, v1
	s_mov_b32 s0, 0x50000
	v_cmp_gt_i32_e32 vcc, s0, v0
	s_and_saveexec_b64 s[0:1], vcc
	s_cbranch_execz .LBB0_203
	s_lshl_b32 s7, s4, 5
	v_readlane_b32 s8, v255, 19
	s_add_u32 s2, s48, 0x8800000
	v_readlane_b32 s4, v253, 59
	v_readlane_b32 s9, v255, 20
	s_addc_u32 s3, s49, 0
	s_add_i32 s12, s5, 8
	v_lshl_add_u32 v10, v1, 3, s4
	s_lshl_b64 s[4:5], s[8:9], 21
	v_readlane_b32 s6, v254, 13
	v_ashrrev_i32_e32 v1, 31, v0
	s_add_u32 s4, s6, s4
	v_readlane_b32 s6, v254, 14
	v_lshlrev_b64 v[2:3], 5, v[0:1]
	s_addc_u32 s5, s6, s5
	v_lshl_add_u64 v[2:3], s[4:5], 0, v[2:3]
	s_lshl_b64 s[4:5], s[8:9], 20
	v_readlane_b32 s8, v255, 17
	v_readlane_b32 s9, v255, 18
	s_add_u32 s4, s8, s4
	s_addc_u32 s5, s9, s5
	v_readlane_b32 s6, v254, 17
	s_add_u32 s4, s6, s4
	v_readlane_b32 s6, v254, 18
	s_addc_u32 s5, s6, s5
	v_lshl_add_u64 v[4:5], v[0:1], 4, s[4:5]
	s_mov_b64 s[8:9], 0
	s_branch .LBB0_201

; #define LAS __attribute__((address_space(3)))
; #define LAS __attribute__((address_space(3)))
; __device__ __forceinline__ int perm_in(int nd) {
;     const int pn = nd >> 8, p = nd & 255, bj = p >> 7, wc = (p >> 5) & 3, i = p & 31;
;     if (pn == 4 || pn == 5) return (bj ? 1280 : 1024) + (pn - 4) * 128 + wc * 32 + i;
;     return pn * 256 + wc * 64 + bj * 32 + i;
; }
; __device__ __forceinline__ int perm_gu(int nd) { const int pn = nd >> 8, p = nd & 255; return (p < 128) ? pn * 128 + p : DFF + pn * 128 + (p - 128); }
; __device__ __forceinline__ void convert_layer_weights(const Args& a, unsigned char* ws, LAS float* scr, int l, int gw, int NGW, int lane, int which) {
;     constexpr int C_IN = 896, C_OUT = 512, C_GU = 2816, C_DN = 1408;
;     const int n_in = (which & 1) ? C_IN : 0, n_out = (which & 2) ? C_OUT : 0, n_gu = (which & 4) ? C_GU : 0, n_dn = (which & 8) ? C_DN : 0;
;     for (int it = gw; it < n_in + n_out + n_gu + n_dn; it += NGW) {
;         int r = it;
;         if (r < n_in) { const int kb = r / 56, nb = r % 56; p0_transpose_item(a.in[9] + (size_t)l * D * INW, INW, D, a.in[8] + l * D, (bf16*)(ws + WS_WIN) + (size_t)l * INW * D, perm_in(32 * nb), 32 * nb, 64 * kb, scr, lane); continue; } r -= n_in;
; __global__ void __launch_bounds__(NWAVES * 64, 2) hymba_fwd(Args args) {
;     ...
;                 if (l + 1 < DEPTH && blockIdx.x >= 64) {
;                     int ln = lane; asm volatile("" : "+v"(ln));
;                     convert_layer_weights(args, ws, (LAS float*)(lds + wave * 16384), l + 1, ((int)blockIdx.x - 64) * NWAVES + wave, (G - 64) * NWAVES, ln, 3);
.LBB0_294:
	v_readlane_b32 s2, v251, 31
	s_cmp_gt_i32 s54, 15
	v_readlane_b32 s3, v251, 32
	s_cselect_b64 s[0:1], -1, 0
	s_xor_b64 s[2:3], s[2:3], -1
	s_or_b64 s[0:1], s[2:3], s[0:1]
	v_readlane_b32 s94, v255, 12
	s_and_b64 vcc, exec, s[0:1]
	v_readlane_b32 s92, v255, 11
	v_readlane_b32 s95, v255, 13
	v_readlane_b32 s6, v251, 40
	v_readlane_b32 s93, v255, 16
	v_readlane_b32 s18, v254, 30
	v_readlane_b32 s19, v254, 35
	s_movk_i32 s29, 0x5800
	s_cbranch_vccnz .LBB0_440
	v_readlane_b32 s0, v251, 33
	v_readlane_b32 s1, v251, 34
	v_and_b32_e32 v0, 63, v216
	s_andn2_b64 vcc, exec, s[0:1]
	s_cbranch_vccnz .LBB0_435
	v_readlane_b32 s100, v255, 19
	s_add_i32 s100, s100, 1
	s_lshl_b32 s100, s100, 8
	s_or_b32 s100, s100, 0x400003
	s_mov_b32 s101, 3
	s_branch .Lcvt_entry
.Lcvt_entry:
	v_writelane_b32 v183, s0, 0
	v_writelane_b32 v183, s1, 1
	v_writelane_b32 v183, s2, 2
	v_writelane_b32 v183, s3, 3
	v_writelane_b32 v183, s4, 4
	v_writelane_b32 v183, s5, 5
	v_writelane_b32 v183, s6, 6
	v_writelane_b32 v183, s7, 7
	v_writelane_b32 v183, s8, 8
	v_writelane_b32 v183, s9, 9
	v_writelane_b32 v183, s10, 10
	v_writelane_b32 v183, s11, 11
	v_writelane_b32 v183, s12, 12
	v_writelane_b32 v183, s13, 13
	v_writelane_b32 v183, s14, 14
	v_writelane_b32 v183, s15, 15
	v_writelane_b32 v183, s16, 16
	v_writelane_b32 v183, s17, 17
	v_writelane_b32 v183, s18, 18
	v_writelane_b32 v183, s19, 19
	v_writelane_b32 v183, s20, 20
	v_writelane_b32 v183, s21, 21
	v_writelane_b32 v183, s22, 22
	v_writelane_b32 v183, s23, 23
	v_writelane_b32 v183, s24, 24
	v_writelane_b32 v183, s25, 25
	v_writelane_b32 v183, s26, 26
	v_writelane_b32 v183, s27, 27
	v_writelane_b32 v183, s28, 28
	v_writelane_b32 v183, s29, 29
	v_writelane_b32 v183, s30, 30
	v_writelane_b32 v183, s31, 31
	v_writelane_b32 v183, s32, 32
	v_writelane_b32 v183, s33, 33
	v_writelane_b32 v183, s34, 34
	v_writelane_b32 v183, s35, 35
	v_writelane_b32 v183, s36, 36
	v_writelane_b32 v183, s37, 37
	v_writelane_b32 v183, s38, 38
	v_writelane_b32 v183, s39, 39
	v_writelane_b32 v183, s40, 40
	v_writelane_b32 v183, s41, 41
	v_writelane_b32 v183, s42, 42
	v_writelane_b32 v183, s43, 43
	v_writelane_b32 v183, s44, 44
	v_writelane_b32 v183, s45, 45
	v_writelane_b32 v183, s46, 46
	v_writelane_b32 v183, s47, 47
	v_writelane_b32 v183, s48, 48
	v_writelane_b32 v183, s49, 49
	v_writelane_b32 v183, s50, 50
	v_writelane_b32 v183, s51, 51
	v_writelane_b32 v183, s52, 52
	v_writelane_b32 v183, s53, 53
	v_writelane_b32 v183, s54, 54
	v_writelane_b32 v183, s55, 55
	v_writelane_b32 v183, s56, 56
	v_writelane_b32 v183, s57, 57
	v_writelane_b32 v183, s58, 58
	v_writelane_b32 v183, s59, 59
	v_writelane_b32 v183, s60, 60
	v_writelane_b32 v183, s61, 61
	v_writelane_b32 v183, s62, 62
	v_writelane_b32 v183, s63, 63
	v_writelane_b32 v182, s64, 0
	v_writelane_b32 v182, s65, 1
	v_writelane_b32 v182, s66, 2
	v_writelane_b32 v182, s67, 3
	s_mov_b64 s[64:65], exec
	v_writelane_b32 v182, s64, 4
	v_writelane_b32 v182, s65, 5
	s_mov_b64 exec, -1
	v_readlane_b32 s0, v251, 3
	v_readlane_b32 s1, v251, 4
	s_sub_u32 s0, s0, 0xd0
	s_subb_u32 s1, s1, 0
	s_load_dwordx2 s[2:3], s[0:1], 0xc0
	s_load_dword s20, s[0:1], 0xd0
	s_load_dwordx2 s[36:37], s[0:1], 0x20
	s_load_dwordx2 s[38:39], s[0:1], 0x38
	s_load_dwordx4 s[40:43], s[0:1], 0x40
	s_load_dwordx4 s[44:47], s[0:1], 0x70
	s_load_dwordx4 s[48:51], s[0:1], 0x90
	s_load_dwordx4 s[52:55], s[0:1], 0xa0
	s_load_dwordx2 s[56:57], s[0:1], 0xb0
	v_readlane_b32 s21, v251, 0
	v_readfirstlane_b32 s22, v216
	s_lshr_b32 s22, s22, 6
	s_lshr_b32 s23, s100, 16
	s_bfe_u32 s7, s100, 0x80008
	v_and_b32_e32 v180, 31, v216
	v_bfe_u32 v179, v216, 5, 1
	v_lshlrev_b32_e32 v177, 7, v179
	s_waitcnt lgkmcnt(0)
	s_sub_i32 s21, s21, s23
	s_sub_i32 s20, s20, s23
	s_lshl_b32 s4, s21, 3
	s_add_i32 s4, s4, s22
	s_lshl_b32 s5, s20, 3
	s_bitcmp1_b32 s100, 0
	s_cselect_b32 s60, 0x380, 0
	s_bitcmp1_b32 s100, 1
	s_cselect_b32 s16, 0x200, 0
	s_add_i32 s61, s60, s16
	s_bitcmp1_b32 s100, 2
	s_cselect_b32 s16, 0xb00, 0
	s_add_i32 s62, s61, s16
	s_bitcmp1_b32 s100, 3
	s_cselect_b32 s16, 0x580, 0
	s_add_i32 s63, s62, s16
	s_bitcmp1_b32 s100, 4
	s_cselect_b32 s16, 0x400, 0
	s_add_i32 s64, s63, s16
	s_bitcmp1_b32 s100, 5
	s_cselect_b32 s16, 0x400, 0
	s_add_i32 s65, s64, s16
	s_bitcmp1_b32 s100, 6
	s_cselect_b32 s16, 0x100, 0
	s_add_i32 s66, s65, s16
.Lcvt_next:
	s_cmp_ge_i32 s4, s66
	s_cbranch_scc1 .Lcvt_exit
	s_cmp_lt_i32 s4, s60
	s_cbranch_scc1 .Lcvt_d0
	s_cmp_lt_i32 s4, s61
	s_cbranch_scc1 .Lcvt_d1
	s_cmp_lt_i32 s4, s62
	s_cbranch_scc1 .Lcvt_d2
	s_cmp_lt_i32 s4, s63
	s_cbranch_scc1 .Lcvt_d3
	s_cmp_lt_i32 s4, s64
	s_cbranch_scc1 .Lcvt_d4
	s_cmp_lt_i32 s4, s65
	s_cbranch_scc1 .Lcvt_d5
	s_branch .Lcvt_d6
.Lcvt_d0:
	s_mul_hi_u32 s16, s4, 0x4924925
	s_mul_i32 s17, s16, 56
	s_sub_i32 s17, s4, s17
	s_lshr_b32 s18, s17, 3
	s_bfe_u32 s19, s17, 0x10002
	s_and_b32 s20, s17, 3
	s_lshl_b32 s21, s18, 8
	s_lshl_b32 s22, s20, 6
	s_add_i32 s21, s21, s22
	s_lshl_b32 s22, s19, 5
	s_add_i32 s21, s21, s22
	s_sub_i32 s22, s18, 4
	s_cmp_lt_u32 s22, 2
	s_cbranch_scc0 .Lcvt_d0a
	s_lshl_b32 s21, s19, 8
	s_addk_i32 s21, 0x400
	s_lshl_b32 s22, s22, 7
	s_add_i32 s21, s21, s22
	s_lshl_b32 s22, s20, 5
	s_add_i32 s21, s21, s22
.Lcvt_d0a:
	s_mul_i32 s22, s7, 0x700000
	s_mul_i32 s23, s16, 0x70000
	s_add_i32 s22, s22, s23
	s_lshl_b32 s23, s21, 2
	s_add_i32 s22, s22, s23
	s_add_u32 s8, s42, s22
	s_addc_u32 s9, s43, 0
	s_movk_i32 s10, 0x1c00
	s_movk_i32 s11, 0x800
	s_lshl_b32 s22, s7, 12
	s_lshl_b32 s23, s16, 8
	s_add_i32 s22, s22, s23
	s_add_u32 s12, s40, s22
	s_addc_u32 s13, s41, 0
	s_mov_b32 s28, 1
	s_mul_i32 s22, s7, 0x380000
	s_lshl_b32 s23, s17, 16
	s_add_i32 s22, s22, s23
	s_lshl_b32 s23, s16, 7
	s_add_i32 s22, s22, s23
	s_add_i32 s22, s22, 0x100000
	s_add_u32 s14, s2, s22
	s_addc_u32 s15, s3, 0
	s_branch .Lcvt_xpose
; __device__ __forceinline__ int perm_gu(int nd) { const int pn = nd >> 8, p = nd & 255; return (p < 128) ? pn * 128 + p : DFF + pn * 128 + (p - 128); }
; __device__ __forceinline__ void convert_layer_weights(const Args& a, unsigned char* ws, LAS float* scr, int l, int gw, int NGW, int lane, int which) {
;     constexpr int C_IN = 896, C_OUT = 512, C_GU = 2816, C_DN = 1408;
;     const int n_in = (which & 1) ? C_IN : 0, n_out = (which & 2) ? C_OUT : 0, n_gu = (which & 4) ? C_GU : 0, n_dn = (which & 8) ? C_DN : 0;
;     for (int it = gw; it < n_in + n_out + n_gu + n_dn; it += NGW) {
;         int r = it;
;         if (r < n_in) { const int kb = r / 56, nb = r % 56; p0_transpose_item(a.in[9] + (size_t)l * D * INW, INW, D, a.in[8] + l * D, (bf16*)(ws + WS_WIN) + (size_t)l * INW * D, perm_in(32 * nb), 32 * nb, 64 * kb, scr, lane); continue; } r -= n_in;
;         if (r < n_out) { const int kb = r / 32, nb = r % 32; p0_transpose_item(a.in[19] + (size_t)l * D * D, D, D, a.in[18] + l * D, (bf16*)(ws + WS_WOUT) + (size_t)l * D * D, 32 * nb, 32 * nb, 64 * kb, scr, lane); continue; } r -= n_out;
;         if (r < n_gu) { const int kb = r / 176, nb = r % 176; p0_transpose_item(a.in[21] + (size_t)l * D * 2 * DFF, 2 * DFF, D, a.in[20] + l * D, (bf16*)(ws + WS_WGU) + (size_t)l * 2 * DFF * D, perm_gu(32 * nb), 32 * nb, 64 * kb, scr, lane); continue; } r -= n_gu;
;         { const int kb = r / 32, nb = r % 32; p0_transpose_item(a.in[22] + (size_t)l * DFF * D, D, DFF, nullptr, (bf16*)(ws + WS_WDN) + (size_t)l * D * DFF, 32 * nb, 32 * nb, 64 * kb, scr, lane); }
;     }
; }
; __device__ __forceinline__ void convert_layer_caches(const Args& a, unsigned char* ws, LAS float* scr, int l, int gw, int NGW, int gt, int NGT, int lane) {
;     constexpr int C_CMV = 1024, C_CWV = 256;
;     for (int it = gw; it < C_CMV + C_CWV; it += NGW) {
;         int r = it;
;         if (r < C_CMV) { const int b = r / 32, r2 = r % 32, kb = r2 / 8, nb = r2 % 8; p0_transpose_item(a.in[7] + (size_t)(l * NBS + b) * 65536, 256, 256, nullptr, (bf16*)(ws + WS_MVT) + (size_t)(l * 40 + 8 + b) * 65536, 32 * nb, 32 * nb, 64 * kb, scr, lane); continue; } r -= C_CMV;
;         { const int b = r / 8, r2 = r % 8, kb = r2 / 4, nb = r2 % 4; p0_transpose_item(a.in[4] + (size_t)(l * NBS + b) * 16384, 128, 128, nullptr, (bf16*)(ws + WS_CWVT) + (size_t)(l * NBS + b) * 16384, 32 * nb, 32 * nb, 64 * kb, scr, lane); }
.Lcvt_d1:
	s_sub_i32 s16, s4, s60
	s_and_b32 s17, s16, 31
	s_lshr_b32 s16, s16, 5
	s_lshl_b32 s22, s7, 22
	s_lshl_b32 s23, s16, 18
	s_add_i32 s22, s22, s23
	s_lshl_b32 s23, s17, 7
	s_add_i32 s22, s22, s23
	s_add_u32 s8, s50, s22
	s_addc_u32 s9, s51, 0
	s_movk_i32 s10, 0x1000
	s_movk_i32 s11, 0x800
	s_lshl_b32 s22, s7, 12
	s_lshl_b32 s23, s16, 8
	s_add_i32 s22, s22, s23
	s_add_u32 s12, s48, s22
	s_addc_u32 s13, s49, 0
	s_mov_b32 s28, 1
	s_lshl_b32 s22, s7, 21
	s_lshl_b32 s23, s17, 16
	s_add_i32 s22, s22, s23
	s_lshl_b32 s23, s16, 7
	s_add_i32 s22, s22, s23
	s_add_i32 s22, s22, 0xf00000
	s_add_u32 s14, s2, s22
	s_addc_u32 s15, s3, 0
	s_branch .Lcvt_xpose
.Lcvt_d2:
	s_sub_i32 s18, s4, s61
	s_mul_hi_u32 s16, s18, 0x1745d18
	s_mul_i32 s17, s16, 0xb0
	s_sub_i32 s17, s18, s17
	s_lshr_b32 s18, s17, 3
	s_lshl_b32 s21, s18, 7
	s_and_b32 s19, s17, 3
	s_lshl_b32 s19, s19, 5
	s_add_i32 s21, s21, s19
	s_bfe_u32 s19, s17, 0x10002
	s_mul_i32 s19, s19, 0xb00
	s_add_i32 s21, s21, s19
	s_mul_i32 s22, s7, 0x1600000
	s_mul_i32 s23, s16, 0x160000
	s_add_i32 s22, s22, s23
	s_lshl_b32 s23, s21, 2
	s_add_i32 s22, s22, s23
	s_add_u32 s8, s54, s22
	s_addc_u32 s9, s55, 0
	s_movk_i32 s10, 0x5800
	s_movk_i32 s11, 0x800
	s_lshl_b32 s22, s7, 12
	s_lshl_b32 s23, s16, 8
	s_add_i32 s22, s22, s23
	s_add_u32 s12, s52, s22
	s_addc_u32 s13, s53, 0
	s_mov_b32 s28, 1
	s_mul_i32 s22, s7, 0xb00000
	s_lshl_b32 s23, s17, 16
	s_add_i32 s22, s22, s23
	s_lshl_b32 s23, s16, 7
	s_add_i32 s22, s22, s23
	s_add_i32 s22, s22, 0x1700000
	s_add_u32 s14, s2, s22
	s_addc_u32 s15, s3, 0
	s_branch .Lcvt_xpose
.Lcvt_d3:
	s_sub_i32 s16, s4, s62
	s_and_b32 s17, s16, 31
	s_lshr_b32 s16, s16, 5
	s_mul_i32 s22, s7, 0xb00000
	s_lshl_b32 s23, s16, 18
	s_add_i32 s22, s22, s23
	s_lshl_b32 s23, s17, 7
	s_add_i32 s22, s22, s23
	s_add_u32 s8, s56, s22
	s_addc_u32 s9, s57, 0
	s_movk_i32 s10, 0x1000
	s_movk_i32 s11, 0x1600
	s_mov_b32 s28, 0
	s_mul_i32 s22, s7, 0x580000
	s_mul_i32 s23, s17, 0x2c000
	s_add_i32 s22, s22, s23
	s_lshl_b32 s23, s16, 7
	s_add_i32 s22, s22, s23
	s_add_i32 s22, s22, 0x4300000
	s_add_u32 s14, s2, s22
	s_addc_u32 s15, s3, 0
	s_branch .Lcvt_xpose
.Lcvt_d4:
	s_sub_i32 s16, s4, s63
	s_lshr_b32 s18, s16, 8
	s_bfe_u32 s17, s16, 0x40000
	s_bfe_u32 s16, s16, 0x40004
	s_lshr_b32 s21, s17, 3
	s_lshl_b32 s21, s21, 8
	s_and_b32 s19, s17, 3
	s_lshl_b32 s19, s19, 6
	s_add_i32 s21, s21, s19
	s_bfe_u32 s19, s17, 0x10002
	s_lshl_b32 s19, s19, 5
	s_add_i32 s21, s21, s19
	s_lshl_b32 s22, s18, 21
	s_lshl_b32 s23, s16, 17
	s_add_i32 s22, s22, s23
	s_lshl_b32 s23, s21, 2
	s_add_i32 s22, s22, s23
	s_add_u32 s8, s46, s22
	s_addc_u32 s9, s47, 0
	s_movk_i32 s10, 0x800
	s_movk_i32 s11, 0x800
	s_lshl_b32 s22, s18, 12
	s_lshl_b32 s23, s16, 8
	s_add_i32 s22, s22, s23
	s_add_u32 s12, s44, s22
	s_addc_u32 s13, s45, 0
	s_mov_b32 s28, 1
	s_lshl_b32 s22, s18, 20
	s_lshl_b32 s23, s17, 16
	s_add_i32 s22, s22, s23
	s_lshl_b32 s23, s16, 7
	s_add_i32 s22, s22, s23
	s_add_i32 s22, s22, 0x5900000
	s_add_u32 s14, s2, s22
	s_addc_u32 s15, s3, 0
	s_branch .Lcvt_xpose
.Lcvt_d5:
	s_sub_i32 s16, s4, s64
	s_lshr_b32 s18, s16, 5
	s_and_b32 s17, s16, 7
	s_bfe_u32 s16, s16, 0x20003
	s_lshl_b32 s19, s7, 5
	s_add_i32 s19, s19, s18
	s_lshl_b32 s22, s19, 18
	s_lshl_b32 s23, s16, 16
	s_add_i32 s22, s22, s23
	s_lshl_b32 s23, s17, 7
	s_add_i32 s22, s22, s23
	s_add_u32 s8, s38, s22
	s_addc_u32 s9, s39, 0
	s_movk_i32 s10, 0x400
	s_movk_i32 s11, 0x200
	s_mov_b32 s28, 0
	s_mul_i32 s19, s7, 40
	s_add_i32 s19, s19, s18
	s_add_i32 s19, s19, 8
	s_lshl_b32 s22, s19, 17
	s_lshl_b32 s23, s17, 14
	s_add_i32 s22, s22, s23
	s_lshl_b32 s23, s16, 7
	s_add_i32 s22, s22, s23
	s_add_i32 s22, s22, 0x9c00000
	s_add_u32 s14, s2, s22
	s_addc_u32 s15, s3, 0
	s_branch .Lcvt_xpose
.Lcvt_d6:
	s_sub_i32 s16, s4, s65
	s_lshr_b32 s18, s16, 3
	s_and_b32 s17, s16, 3
	s_bfe_u32 s16, s16, 0x10002
	s_lshl_b32 s19, s7, 5
	s_add_i32 s19, s19, s18
	s_lshl_b32 s22, s19, 16
	s_lshl_b32 s23, s16, 15
	s_add_i32 s22, s22, s23
	s_lshl_b32 s23, s17, 7
	s_add_i32 s22, s22, s23
	s_add_u32 s8, s36, s22
	s_addc_u32 s9, s37, 0
	s_movk_i32 s10, 0x200
	s_movk_i32 s11, 0x100
	s_mov_b32 s28, 0
	s_lshl_b32 s22, s19, 15
	s_lshl_b32 s23, s17, 13
	s_add_i32 s22, s22, s23
	s_lshl_b32 s23, s16, 7
	s_add_i32 s22, s22, s23
	s_add_i32 s22, s22, 0xb400000
	s_add_u32 s14, s2, s22
	s_addc_u32 s15, s3, 0
; #define LAS __attribute__((address_space(3)))
; #define LAS __attribute__((address_space(3)))
; __device__ __forceinline__ void p0_transpose_item(const float* W, int ldw, int K, const float* gain, bf16* WT, int n0src, int n0dst, int k0, LAS float* scr, int lane) {
; #pragma unroll
;     for (int i = 0; i < 32; ++i) {
;         const int kk = 2 * i + (lane >> 5);
;         float w = __builtin_nontemporal_load(&W[(size_t)(k0 + kk) * ldw + n0src + (lane & 31)]);
;         if (gain) w *= gain[k0 + kk];
;         scr[kk * 33 + (lane & 31)] = w;
;     }
.Lcvt_xpose:
	s_lshl_b32 s16, s10, 5
	v_mul_lo_u32 v176, v179, s16
	v_lshl_add_u32 v176, v180, 2, v176
	global_load_dword v96, v176, s[8:9] nt
	v_add_u32_e32 v176, s10, v176
	global_load_dword v97, v176, s[8:9] nt
	v_add_u32_e32 v176, s10, v176
	global_load_dword v98, v176, s[8:9] nt
	v_add_u32_e32 v176, s10, v176
	global_load_dword v99, v176, s[8:9] nt
	v_add_u32_e32 v176, s10, v176
	global_load_dword v100, v176, s[8:9] nt
	v_add_u32_e32 v176, s10, v176
	global_load_dword v101, v176, s[8:9] nt
	v_add_u32_e32 v176, s10, v176
	global_load_dword v102, v176, s[8:9] nt
	v_add_u32_e32 v176, s10, v176
	global_load_dword v103, v176, s[8:9] nt
	v_add_u32_e32 v176, s10, v176
	global_load_dword v104, v176, s[8:9] nt
	v_add_u32_e32 v176, s10, v176
	global_load_dword v105, v176, s[8:9] nt
	v_add_u32_e32 v176, s10, v176
	global_load_dword v106, v176, s[8:9] nt
	v_add_u32_e32 v176, s10, v176
	global_load_dword v107, v176, s[8:9] nt
	v_add_u32_e32 v176, s10, v176
	global_load_dword v108, v176, s[8:9] nt
	v_add_u32_e32 v176, s10, v176
	global_load_dword v109, v176, s[8:9] nt
	v_add_u32_e32 v176, s10, v176
	global_load_dword v110, v176, s[8:9] nt
	v_add_u32_e32 v176, s10, v176
	global_load_dword v111, v176, s[8:9] nt
	v_add_u32_e32 v176, s10, v176
	global_load_dword v112, v176, s[8:9] nt
	v_add_u32_e32 v176, s10, v176
	global_load_dword v113, v176, s[8:9] nt
	v_add_u32_e32 v176, s10, v176
	global_load_dword v114, v176, s[8:9] nt
	v_add_u32_e32 v176, s10, v176
	global_load_dword v115, v176, s[8:9] nt
	v_add_u32_e32 v176, s10, v176
	global_load_dword v116, v176, s[8:9] nt
	v_add_u32_e32 v176, s10, v176
	global_load_dword v117, v176, s[8:9] nt
	v_add_u32_e32 v176, s10, v176
	global_load_dword v118, v176, s[8:9] nt
	v_add_u32_e32 v176, s10, v176
	global_load_dword v119, v176, s[8:9] nt
	v_add_u32_e32 v176, s10, v176
	global_load_dword v120, v176, s[8:9] nt
	v_add_u32_e32 v176, s10, v176
	global_load_dword v121, v176, s[8:9] nt
	v_add_u32_e32 v176, s10, v176
	global_load_dword v122, v176, s[8:9] nt
	v_add_u32_e32 v176, s10, v176
	global_load_dword v123, v176, s[8:9] nt
	v_add_u32_e32 v176, s10, v176
	global_load_dword v124, v176, s[8:9] nt
	v_add_u32_e32 v176, s10, v176
	global_load_dword v125, v176, s[8:9] nt
	v_add_u32_e32 v176, s10, v176
	global_load_dword v126, v176, s[8:9] nt
	v_add_u32_e32 v176, s10, v176
	global_load_dword v127, v176, s[8:9] nt
	s_cmp_eq_u32 s28, 0
	s_cbranch_scc1 .Lcvt_nogain
	global_load_dwordx4 v[128:131], v177, s[12:13]
	global_load_dwordx4 v[132:135], v177, s[12:13] offset:16
	global_load_dwordx4 v[136:139], v177, s[12:13] offset:32
	global_load_dwordx4 v[140:143], v177, s[12:13] offset:48
	global_load_dwordx4 v[144:147], v177, s[12:13] offset:64
	global_load_dwordx4 v[148:151], v177, s[12:13] offset:80
	global_load_dwordx4 v[152:155], v177, s[12:13] offset:96
	global_load_dwordx4 v[156:159], v177, s[12:13] offset:112
	s_waitcnt vmcnt(0)
	v_mul_f32_e32 v96, v96, v128
	v_mul_f32_e32 v97, v97, v129
	v_mul_f32_e32 v98, v98, v130
	v_mul_f32_e32 v99, v99, v131
	v_mul_f32_e32 v100, v100, v132
	v_mul_f32_e32 v101, v101, v133
	v_mul_f32_e32 v102, v102, v134
	v_mul_f32_e32 v103, v103, v135
	v_mul_f32_e32 v104, v104, v136
	v_mul_f32_e32 v105, v105, v137
	v_mul_f32_e32 v106, v106, v138
	v_mul_f32_e32 v107, v107, v139
	v_mul_f32_e32 v108, v108, v140
	v_mul_f32_e32 v109, v109, v141
	v_mul_f32_e32 v110, v110, v142
	v_mul_f32_e32 v111, v111, v143
	v_mul_f32_e32 v112, v112, v144
	v_mul_f32_e32 v113, v113, v145
	v_mul_f32_e32 v114, v114, v146
	v_mul_f32_e32 v115, v115, v147
	v_mul_f32_e32 v116, v116, v148
	v_mul_f32_e32 v117, v117, v149
	v_mul_f32_e32 v118, v118, v150
	v_mul_f32_e32 v119, v119, v151
	v_mul_f32_e32 v120, v120, v152
	v_mul_f32_e32 v121, v121, v153
	v_mul_f32_e32 v122, v122, v154
	v_mul_f32_e32 v123, v123, v155
	v_mul_f32_e32 v124, v124, v156
	v_mul_f32_e32 v125, v125, v157
	v_mul_f32_e32 v126, v126, v158
	v_mul_f32_e32 v127, v127, v159
	s_branch .Lcvt_pack

; #define LAS __attribute__((address_space(3)))
; #define LAS __attribute__((address_space(3)))
; #define LDS_WAIT() asm volatile("s_waitcnt lgkmcnt(0)" ::: "memory")
; __device__ __forceinline__ unsigned pk2(float lo, float hi) { return pg8::cvt_pk_bf16(lo, hi); }
; __device__ __forceinline__ void p0_transpose_item(const float* W, int ldw, int K, const float* gain, bf16* WT, int n0src, int n0dst, int k0, LAS float* scr, int lane) {
;     ...
;     LDS_WAIT(); asm volatile("" ::: "memory");
;     const int c = lane & 7;
; #pragma unroll
;     for (int j = 0; j < 4; ++j) {
;         const int n = (lane >> 3) + 8 * j; const LAS float* s = scr + (8 * c) * 33 + n;
;         v4u o; o.x = pk2(s[0 * 33], s[1 * 33]); o.y = pk2(s[2 * 33], s[3 * 33]); o.z = pk2(s[4 * 33], s[5 * 33]); o.w = pk2(s[6 * 33], s[7 * 33]);
;         *(v4u*)(WT + (size_t)(n0dst + n) * K + k0 + 8 * c) = o;
;     }
;     LDS_WAIT(); asm volatile("" ::: "memory");
; }
; __device__ __forceinline__ void copy_window_outputs(const Args& a, int gt, int NGT) {
;     for (int i = gt; i < 2 * 128 * 2048; i += NGT) {
;         const int t = i >> 18, r = i & 262143, lb = r >> 11, q = r & 2047;
;         const float* src = (t ? a.in[4] : a.in[3]) + (size_t)lb * 16384 + 8192 + q * 4;
;         float* dst = a.out + (t ? O_WVS : O_WKS) + (size_t)lb * 16384 + q * 4;
;         __builtin_nontemporal_store(__builtin_nontemporal_load((const f32x4*)src), (f32x4*)dst);
;     }
; }
.Lcvt_pack:
	v_cvt_pk_bf16_f32 v160, v96, v97
	v_cvt_pk_bf16_f32 v161, v98, v99
	v_cvt_pk_bf16_f32 v162, v100, v101
	v_cvt_pk_bf16_f32 v163, v102, v103
	v_cvt_pk_bf16_f32 v164, v104, v105
	v_cvt_pk_bf16_f32 v165, v106, v107
	v_cvt_pk_bf16_f32 v166, v108, v109
	v_cvt_pk_bf16_f32 v167, v110, v111
	v_cvt_pk_bf16_f32 v168, v112, v113
	v_cvt_pk_bf16_f32 v169, v114, v115
	v_cvt_pk_bf16_f32 v170, v116, v117
	v_cvt_pk_bf16_f32 v171, v118, v119
	v_cvt_pk_bf16_f32 v172, v120, v121
	v_cvt_pk_bf16_f32 v173, v122, v123
	v_cvt_pk_bf16_f32 v174, v124, v125
	v_cvt_pk_bf16_f32 v175, v126, v127
	v_mul_lo_u32 v178, v180, s11
	v_lshl_add_u32 v178, v179, 6, v178
	global_store_dwordx4 v178, v[160:163], s[14:15]
	global_store_dwordx4 v178, v[164:167], s[14:15] offset:16
	global_store_dwordx4 v178, v[168:171], s[14:15] offset:32
	global_store_dwordx4 v178, v[172:175], s[14:15] offset:48
	s_add_i32 s4, s4, s5
	s_branch .Lcvt_next
.Lcvt_exit:
	v_readlane_b32 s64, v182, 4
	v_readlane_b32 s65, v182, 5
	s_nop 1
	s_mov_b64 exec, s[64:65]
	v_readlane_b32 s64, v182, 0
	v_readlane_b32 s65, v182, 1
	v_readlane_b32 s66, v182, 2
	v_readlane_b32 s67, v182, 3
	v_readlane_b32 s0, v183, 0
	v_readlane_b32 s1, v183, 1
	v_readlane_b32 s2, v183, 2
	v_readlane_b32 s3, v183, 3
	v_readlane_b32 s4, v183, 4
	v_readlane_b32 s5, v183, 5
	v_readlane_b32 s6, v183, 6
	v_readlane_b32 s7, v183, 7
	v_readlane_b32 s8, v183, 8
	v_readlane_b32 s9, v183, 9
	v_readlane_b32 s10, v183, 10
	v_readlane_b32 s11, v183, 11
	v_readlane_b32 s12, v183, 12
	v_readlane_b32 s13, v183, 13
	v_readlane_b32 s14, v183, 14
	v_readlane_b32 s15, v183, 15
	v_readlane_b32 s16, v183, 16
	v_readlane_b32 s17, v183, 17
	v_readlane_b32 s18, v183, 18
	v_readlane_b32 s19, v183, 19
	v_readlane_b32 s20, v183, 20
	v_readlane_b32 s21, v183, 21
	v_readlane_b32 s22, v183, 22
	v_readlane_b32 s23, v183, 23
	v_readlane_b32 s24, v183, 24
	v_readlane_b32 s25, v183, 25
	v_readlane_b32 s26, v183, 26
	v_readlane_b32 s27, v183, 27
	v_readlane_b32 s28, v183, 28
	v_readlane_b32 s29, v183, 29
	v_readlane_b32 s30, v183, 30
	v_readlane_b32 s31, v183, 31
	v_readlane_b32 s32, v183, 32
	v_readlane_b32 s33, v183, 33
	v_readlane_b32 s34, v183, 34
	v_readlane_b32 s35, v183, 35
	v_readlane_b32 s36, v183, 36
	v_readlane_b32 s37, v183, 37
	v_readlane_b32 s38, v183, 38
	v_readlane_b32 s39, v183, 39
	v_readlane_b32 s40, v183, 40
	v_readlane_b32 s41, v183, 41
	v_readlane_b32 s42, v183, 42
	v_readlane_b32 s43, v183, 43
	v_readlane_b32 s44, v183, 44
	v_readlane_b32 s45, v183, 45
	v_readlane_b32 s46, v183, 46
	v_readlane_b32 s47, v183, 47
	v_readlane_b32 s48, v183, 48
	v_readlane_b32 s49, v183, 49
	v_readlane_b32 s50, v183, 50
	v_readlane_b32 s51, v183, 51
	v_readlane_b32 s52, v183, 52
	v_readlane_b32 s53, v183, 53
	v_readlane_b32 s54, v183, 54
	v_readlane_b32 s55, v183, 55
	v_readlane_b32 s56, v183, 56
	v_readlane_b32 s57, v183, 57
	v_readlane_b32 s58, v183, 58
	v_readlane_b32 s59, v183, 59
	v_readlane_b32 s60, v183, 60
	v_readlane_b32 s61, v183, 61
	v_readlane_b32 s62, v183, 62
	v_readlane_b32 s63, v183, 63
	s_nop 4
	s_cmp_eq_u32 s101, 1
	s_cbranch_scc1 .Lcvt_ret1
	s_cmp_eq_u32 s101, 2
	s_cbranch_scc1 .Lcvt_ret2
	s_cmp_eq_u32 s101, 3
	s_cbranch_scc1 .Lcvt_ret3
	s_cmp_eq_u32 s101, 4
	s_cbranch_scc1 .Lcvt_ret4
	s_cmp_eq_u32 s101, 5
	s_cbranch_scc1 .Lcvt_ret5
	s_cmp_eq_u32 s101, 6
	s_cbranch_scc1 .Lcvt_ret6
	s_branch .Lcvt_ret7
.Lcvt_ret3:
.LBB0_435:
	s_add_i32 s0, s54, 3
	s_cmp_gt_u32 s0, 8
	s_cbranch_scc1 .LBB0_440
	v_mov_b32_e32 v0, v216
	v_readlane_b32 s0, v251, 38
	s_nop 1
	v_add_u32_e32 v0, s0, v0
	s_mov_b32 s0, 0x80000
	v_cmp_gt_i32_e32 vcc, s0, v0
	s_mov_b64 s[0:1], exec
	s_and_b64 s[2:3], s[0:1], vcc
	v_mov_b32_e32 v12, 0x6410000
	v_mov_b32_e32 v13, 0x5c10000
	s_mov_b64 exec, s[2:3]
	s_cbranch_execz .LBB0_439
	v_lshlrev_b32_e32 v1, 2, v0
	v_lshlrev_b32_e32 v2, 3, v0
	s_mov_b64 s[2:3], 0

; #define LAS __attribute__((address_space(3)))
; #define LAS __attribute__((address_space(3)))
; __device__ __forceinline__ void p0_prologue(const Args& a, unsigned char* ws, LAS unsigned char* lds, int tid_in, int lane_in, int wave) {
;     int tid = tid_in, lane = lane_in; asm volatile("" : "+v"(tid), "+v"(lane));
;     LAS float* scr = (LAS float*)(lds + wave * 16384);
;     const int G = gridDim.x, gw = blockIdx.x * NWAVES + wave, NGW = G * NWAVES;
;     convert_layer_weights(a, ws, scr, 0, gw, NGW, lane, 1);
; __global__ void __launch_bounds__(NWAVES * 64, 2) hymba_fwd(Args args) {
;     ...
;                 if (l == 0 && blockIdx.x >= 64) {
;                     int ln = lane; asm volatile("" : "+v"(ln));
;                     convert_layer_weights(args, ws, (LAS float*)(lds + wave * 16384), 0, ((int)blockIdx.x - 64) * NWAVES + wave, (G - 64) * NWAVES, ln, 14);
;                 }
.LBB0_699:
	v_readlane_b32 s0, v251, 31
	v_readlane_b32 s1, v251, 32
	s_and_b64 s[0:1], s[0:1], s[50:51]
	s_andn2_b64 vcc, exec, s[0:1]
	s_cbranch_vccnz .LBB0_912
	v_readlane_b32 s0, v251, 61
	v_readlane_b32 s1, v251, 62
	v_and_b32_e32 v0, 63, v216
	s_andn2_b64 vcc, exec, s[0:1]
	s_cbranch_vccnz .LBB0_912
	s_mov_b32 s100, 0x40000e
	s_mov_b32 s101, 4
	s_branch .Lcvt_entry
.Lcvt_ret4:
.LBB0_912:
	s_mov_b64 s[0:1], 0
.LBB0_913:
	s_and_b64 vcc, exec, s[0:1]
	s_cbranch_vccz .LBB0_986
	v_readlane_b32 s0, v251, 63
	v_readlane_b32 s1, v252, 0
	v_mov_b32_e32 v32, v216
	v_and_b32_e32 v34, 63, v216
	s_andn2_b64 vcc, exec, s[0:1]
	s_cbranch_vccnz .LBB0_987
	s_mov_b32 s100, 0x1
	s_mov_b32 s101, 5
	s_branch .Lcvt_entry

; __device__ __forceinline__ unsigned pk2(float lo, float hi) { return pg8::cvt_pk_bf16(lo, hi); }
; __device__ __forceinline__ void convert_layer_caches(const Args& a, unsigned char* ws, LAS float* scr, int l, int gw, int NGW, int gt, int NGT, int lane) {
;     ...
;     for (int i = gt; i < (524288 + 2097152) / 8; i += NGT) {
;         const float* src; bf16* dst;
;         if (i < 65536) { const size_t e = (size_t)l * 524288 + (size_t)i * 8; src = a.in[3] + e; dst = (bf16*)(ws + WS_CWK) + e; }
;         else { const int e = (i - 65536) * 8, b = e >> 16, rem = e & 65535; src = a.in[6] + (size_t)(l * NBS + b) * 65536 + rem; dst = (bf16*)(ws + WS_MK) + (size_t)(l * 40 + 8 + b) * 65536 + rem; }
;         const f32x4 x0 = __builtin_nontemporal_load((const f32x4*)src), x1 = __builtin_nontemporal_load((const f32x4*)(src + 4));
;         v4u o; o.x = pk2(x0.x, x0.y); o.y = pk2(x0.z, x0.w); o.z = pk2(x1.x, x1.y); o.w = pk2(x1.z, x1.w);
;         *(v4u*)dst = o;
;     }
; __device__ __forceinline__ void p0_prologue(const Args& a, unsigned char* ws, LAS unsigned char* lds, int tid_in, int lane_in, int wave) {
;     ...
;     for (int it = gw; it < DEPTH * 256; it += NGW) {
;         const int l = it >> 8, r = it & 255, kb = r / 16, nb = r % 16;
;         p0_transpose_item(a.in[15] + (size_t)l * D * 512, 512, D, a.in[14] + l * D, (bf16*)(ws + WS_WMEM) + (size_t)l * 512 * D, perm_mem(32 * nb), 32 * nb, 64 * kb, scr, lane);
;     }
;     convert_layer_caches(a, ws, scr, 0, gw, NGW, blockIdx.x * (NWAVES * 64) + tid, G * NWAVES * 64, lane);
.Lcvt_ret5:
.LBB0_987:
	v_readlane_b32 s0, v252, 1
	v_readlane_b32 s1, v252, 2
	s_andn2_b64 vcc, exec, s[0:1]
	s_cbranch_vccnz .LBB0_1054
	s_mov_b32 s100, 0x10
	s_mov_b32 s101, 6
	s_branch .Lcvt_entry
.Lcvt_ret6:
.LBB0_1054:
	v_readlane_b32 s0, v252, 21
	v_readlane_b32 s1, v252, 22
	s_andn2_b64 vcc, exec, s[0:1]
	s_cbranch_vccnz .LBB0_1061
	s_mov_b32 s100, 0x60
	s_mov_b32 s101, 7
	s_branch .Lcvt_entry
.Lcvt_ret7:
.LBB0_1061:
	v_readlane_b32 s0, v251, 37
	s_nop 1
	v_add_u32_e32 v0, s0, v32
	s_mov_b32 s0, 0x50000
	v_cmp_gt_i32_e32 vcc, s0, v0
	s_and_saveexec_b64 s[0:1], vcc
	s_cbranch_execz .LBB0_1066
	s_add_u32 s2, s48, 0x8800000
	v_readlane_b32 s4, v253, 58
	s_addc_u32 s3, s49, 0
	v_readlane_b32 s6, v255, 17
	v_lshl_add_u32 v10, v32, 3, s4
	v_readlane_b32 s4, v254, 53
	v_ashrrev_i32_e32 v1, 31, v0
	v_readlane_b32 s7, v255, 18
	s_add_u32 s4, s4, s6
	v_readlane_b32 s5, v254, 54
	v_lshlrev_b64 v[2:3], 5, v[0:1]
	s_addc_u32 s5, s5, s7
	v_lshl_add_u64 v[2:3], s[82:83], 0, v[2:3]
	v_lshl_add_u64 v[4:5], v[0:1], 4, s[4:5]
	s_mov_b64 s[8:9], 0
	s_branch .LBB0_1064

; #define LAS __attribute__((address_space(3)))
; #define LAS __attribute__((address_space(3)))
; __global__ void __launch_bounds__(NWAVES * 64, 2) hymba_fwd(Args args) {
;     extern __shared__ __attribute__((aligned(16))) unsigned char lds_raw[];
;     LAS unsigned char* lds = (LAS unsigned char*)lds_raw;
;     const int tid = threadIdx.x, lane = tid & 63, wave = __builtin_amdgcn_readfirstlane(tid >> 6);
	.amdhsa_kernel _Z9hymba_fwd4Args
		.amdhsa_group_segment_fixed_size 0
		.amdhsa_private_segment_fixed_size 0
		.amdhsa_kernarg_size 464
		.amdhsa_user_sgpr_count 2
		.amdhsa_user_sgpr_dispatch_ptr 0
		.amdhsa_user_sgpr_queue_ptr 0
		.amdhsa_user_sgpr_kernarg_segment_ptr 1
		.amdhsa_user_sgpr_dispatch_id 0
		.amdhsa_user_sgpr_kernarg_preload_length 0
		.amdhsa_user_sgpr_kernarg_preload_offset 0
		.amdhsa_user_sgpr_private_segment_size 0
		.amdhsa_uses_dynamic_stack 0
		.amdhsa_enable_private_segment 0
		.amdhsa_system_sgpr_workgroup_id_x 1
		.amdhsa_system_sgpr_workgroup_id_y 0
		.amdhsa_system_sgpr_workgroup_id_z 0
		.amdhsa_system_sgpr_workgroup_info 0
		.amdhsa_system_vgpr_workitem_id 2
		.amdhsa_next_free_vgpr 256
		.amdhsa_next_free_sgpr 102
		.amdhsa_accum_offset 256
		.amdhsa_reserve_vcc 1
		.amdhsa_float_round_mode_32 0
		.amdhsa_float_round_mode_16_64 0
		.amdhsa_float_denorm_mode_32 3
		.amdhsa_float_denorm_mode_16_64 3
		.amdhsa_dx10_clamp 1
		.amdhsa_ieee_mode 1
		.amdhsa_fp16_overflow 0
		.amdhsa_tg_split 0
		.amdhsa_exception_fp_ieee_invalid_op 0
		.amdhsa_exception_fp_denorm_src 0
		.amdhsa_exception_fp_ieee_div_zero 0
		.amdhsa_exception_fp_ieee_overflow 0
		.amdhsa_exception_fp_ieee_underflow 0
		.amdhsa_exception_fp_ieee_inexact 0
		.amdhsa_exception_int_div_zero 0
	.end_amdhsa_kernel

; #define LAS __attribute__((address_space(3)))
; #define LAS __attribute__((address_space(3)))
; __global__ void __launch_bounds__(NWAVES * 64, 2) hymba_fwd(Args args) {
;     extern __shared__ __attribute__((aligned(16))) unsigned char lds_raw[];
;     LAS unsigned char* lds = (LAS unsigned char*)lds_raw;
;     const int tid = threadIdx.x, lane = tid & 63, wave = __builtin_amdgcn_readfirstlane(tid >> 6);
.Lfunc_end0:
	.size	_Z9hymba_fwd4Args, .Lfunc_end0-_Z9hymba_fwd4Args
	.set _Z9hymba_fwd4Args.num_vgpr, 256
	.set _Z9hymba_fwd4Args.num_agpr, 0
	.set _Z9hymba_fwd4Args.numbered_sgpr, 102
	.set _Z9hymba_fwd4Args.num_named_barrier, 0
	.set _Z9hymba_fwd4Args.private_seg_size, 0
	.set _Z9hymba_fwd4Args.uses_vcc, 1
	.set _Z9hymba_fwd4Args.uses_flat_scratch, 0
	.set _Z9hymba_fwd4Args.has_dyn_sized_stack, 0
	.set _Z9hymba_fwd4Args.has_recursion, 0
	.set _Z9hymba_fwd4Args.has_indirect_call, 0

; #define LAS __attribute__((address_space(3)))
; #define LAS __attribute__((address_space(3)))
; __global__ void __launch_bounds__(NWAVES * 64, 2) hymba_fwd(Args args) {
;     extern __shared__ __attribute__((aligned(16))) unsigned char lds_raw[];
;     LAS unsigned char* lds = (LAS unsigned char*)lds_raw;
;     const int tid = threadIdx.x, lane = tid & 63, wave = __builtin_amdgcn_readfirstlane(tid >> 6);
amdhsa.kernels:
  - .agpr_count:     0
    .args:
      - .offset:         0
        .size:           208
        .value_kind:     by_value
      - .offset:         208
        .size:           4
        .value_kind:     hidden_block_count_x
      - .offset:         212
        .size:           4
        .value_kind:     hidden_block_count_y
      - .offset:         216
        .size:           4
        .value_kind:     hidden_block_count_z
      - .offset:         220
        .size:           2
        .value_kind:     hidden_group_size_x
      - .offset:         222
        .size:           2
        .value_kind:     hidden_group_size_y
      - .offset:         224
        .size:           2
        .value_kind:     hidden_group_size_z
      - .offset:         226
        .size:           2
        .value_kind:     hidden_remainder_x
      - .offset:         228
        .size:           2
        .value_kind:     hidden_remainder_y
      - .offset:         230
        .size:           2
        .value_kind:     hidden_remainder_z
      - .offset:         248
        .size:           8
        .value_kind:     hidden_global_offset_x
      - .offset:         256
        .size:           8
        .value_kind:     hidden_global_offset_y
      - .offset:         264
        .size:           8
        .value_kind:     hidden_global_offset_z
      - .offset:         272
        .size:           2
        .value_kind:     hidden_grid_dims
      - .offset:         296
        .size:           8
        .value_kind:     hidden_multigrid_sync_arg
      - .offset:         328
        .size:           4
        .value_kind:     hidden_dynamic_lds_size
    .group_segment_fixed_size: 0
    .kernarg_segment_align: 8
    .kernarg_segment_size: 464
    .language:       OpenCL C
    .language_version:
      - 2
      - 0
    .max_flat_workgroup_size: 512
    .name:           _Z9hymba_fwd4Args
    .private_segment_fixed_size: 0
    .sgpr_count:     108
    .sgpr_spill_count: 306
    .symbol:         _Z9hymba_fwd4Args.kd
    .uniform_work_group_size: 1
    .uses_dynamic_stack: false
    .vgpr_count:     256
    .vgpr_spill_count: 0
    .wavefront_size: 64
